# k13 plus: conv-FFN gate phase issues its per-column weight loads at the top of each item (before the activation loads)
# speedup vs baseline: 1.0078x; 1.0016x over previous
; __device__ __forceinline__ unsigned cvt_pk_bf16(float lo, float hi) { unsigned r; asm volatile("v_cvt_pk_bf16_f32 %0, %1, %2" : "=v"(r) : "v"(lo), "v"(hi)); return r; }
; __device__ __forceinline__ float gelu_erf(float v) {
;     const float av = __builtin_fabsf(v), d = av * 0.2316418882f + 1.0f, t = __builtin_amdgcn_rcpf(d);
;     float q = t * 0.5307027145f + (-0.7265760135f); q = q * t + 0.7107068705f; q = q * t + (-0.142248368f); q = q * t + 0.127414796f; q = q * t;
;     const float e = __builtin_amdgcn_exp2f((v * v) * (-0.72134752044f));
;     const float m = v * (q * e), r = v - m;
;     return v < 0.f ? m : r;
; }
; __global__ void __launch_bounds__(512, 2) mega_fwd(Params p) {
;     ...
;                         const int rr = it / 11, cgp = it - rr * 11, col = (cgp * 64 + lane) * 4, r0 = rr * 8;
;                         u32x2 ra[10], rg[10];
;                         const bool hp = (r0 & smask) != 0, hn = ((r0 + 8) & smask) != 0;
; #pragma unroll
;                         for (int i = 0; i < 10; ++i) {
;                             const bool ok = (i == 0) ? hp : (i == 9) ? hn : true;
;                             if (ok) { ra[i] = *(const u32x2*)(H + (size_t)(r0 - 1 + i) * NFF + col); rg[i] = *(const u32x2*)(H + (size_t)(r0 - 1 + i) * NFF + DFF + col); }
;                             else { ra[i] = (u32x2){0u, 0u}; rg[i] = (u32x2){0u, 0u}; }
;                         }
;                         f32x4 wa[3], wg[3];
; #pragma unroll
;                         for (int k = 0; k < 3; ++k) { wa[k] = *(const f32x4*)(cw + k * NFF + col); wg[k] = *(const f32x4*)(cw + k * NFF + DFF + col); }
;                         const f32x4 ba = *(const f32x4*)(cb + col), bg = *(const f32x4*)(cb + DFF + col);
;     ...
; #pragma unroll
;                         for (int i = 0; i < 8; ++i) {
;                             const f32x4 av = wa[0] * BF4(ra[i]) + wa[1] * BF4(ra[i + 1]) + wa[2] * BF4(ra[i + 2]) + ba;
;                             const f32x4 gv = wg[0] * BF4(rg[i]) + wg[1] * BF4(rg[i + 1]) + wg[2] * BF4(rg[i + 2]) + bg;
;                             u32x2 w; w.x = cvt_pk_bf16(av[0] * gelu_erf(gv[0]), av[1] * gelu_erf(gv[1])); w.y = cvt_pk_bf16(av[2] * gelu_erf(gv[2]), av[3] * gelu_erf(gv[3]));
;                             *(u32x2*)(U + (size_t)(row0 + r0 + i) * DFF + col) = w;
;                         }
.LBB0_1143:
	v_mov_b64_e32 v[4:5], v[100:101]
	v_mov_b64_e32 v[6:7], v[102:103]
	v_mov_b64_e32 v[44:45], v[104:105]
	v_mov_b64_e32 v[46:47], v[106:107]
	v_mov_b64_e32 v[12:13], v[108:109]
	v_mov_b64_e32 v[14:15], v[110:111]
	v_mov_b64_e32 v[48:49], v[112:113]
	v_mov_b64_e32 v[50:51], v[114:115]
	v_mov_b64_e32 v[40:41], v[116:117]
	v_mov_b64_e32 v[42:43], v[118:119]
	v_mov_b64_e32 v[52:53], v[120:121]
	v_mov_b64_e32 v[54:55], v[122:123]
	v_mov_b64_e32 v[0:1], v[124:125]
	v_mov_b64_e32 v[2:3], v[126:127]
	v_mov_b64_e32 v[8:9], v[128:129]
	v_mov_b64_e32 v[10:11], v[130:131]
	v_lshlrev_b32_e32 v74, 16, v76
	v_and_b32_e32 v75, 0xffff0000, v76
	v_lshl_add_u64 v[16:17], v[70:71], 1, s[44:45]
	v_lshlrev_b32_e32 v70, 16, v72
	v_and_b32_e32 v71, 0xffff0000, v72
	v_lshlrev_b32_e32 v76, 16, v77
	v_and_b32_e32 v77, 0xffff0000, v77
	v_lshlrev_b32_e32 v72, 16, v73
	v_and_b32_e32 v73, 0xffff0000, v73
	v_lshlrev_b32_e32 v88, 16, v20
	v_and_b32_e32 v89, 0xffff0000, v20
	v_lshlrev_b32_e32 v20, 16, v21
	v_and_b32_e32 v21, 0xffff0000, v21
	s_add_i32 s16, s0, s39
	s_add_i32 s22, s22, s53
	v_add_u32_e32 v86, s24, v86
	s_waitcnt vmcnt(0)
	v_pk_mul_f32 v[82:83], v[44:45], v[74:75]
	v_pk_mul_f32 v[80:81], v[46:47], v[76:77]
	v_pk_fma_f32 v[82:83], v[4:5], v[70:71], v[82:83]
	v_lshlrev_b32_e32 v70, 16, v78
	v_and_b32_e32 v71, 0xffff0000, v78
	v_pk_fma_f32 v[80:81], v[6:7], v[72:73], v[80:81]
	v_lshlrev_b32_e32 v72, 16, v79
	v_and_b32_e32 v73, 0xffff0000, v79
	s_waitcnt vmcnt(4)
	v_pk_fma_f32 v[82:83], v[48:49], v[70:71], v[82:83]
	v_pk_fma_f32 v[78:79], v[50:51], v[72:73], v[80:81]
	s_waitcnt vmcnt(2)
	v_pk_add_f32 v[84:85], v[52:53], v[82:83]
	v_lshlrev_b32_e32 v80, 16, v22
	v_and_b32_e32 v81, 0xffff0000, v22
	v_lshlrev_b32_e32 v82, 16, v23
	v_and_b32_e32 v83, 0xffff0000, v23
	v_pk_mul_f32 v[22:23], v[14:15], v[82:83]
	v_pk_mul_f32 v[90:91], v[12:13], v[80:81]
	s_waitcnt vmcnt(1)
	v_pk_fma_f32 v[92:93], v[2:3], v[20:21], v[22:23]
	v_pk_fma_f32 v[88:89], v[0:1], v[88:89], v[90:91]
	v_lshlrev_b32_e32 v20, 16, v24
	v_and_b32_e32 v21, 0xffff0000, v24
	v_pk_fma_f32 v[88:89], v[40:41], v[20:21], v[88:89]
	v_lshlrev_b32_e32 v22, 16, v25
	s_waitcnt vmcnt(0)
	v_pk_add_f32 v[88:89], v[8:9], v[88:89]
	v_and_b32_e32 v23, 0xffff0000, v25
	v_fma_f32 v18, |v88|, s33, 1.0
	v_rcp_f32_e32 v18, v18
	v_cmp_gt_f32_e32 vcc, 0, v88
	v_pk_fma_f32 v[24:25], v[42:43], v[22:23], v[92:93]
	v_pk_add_f32 v[78:79], v[54:55], v[78:79]
	v_fmamk_f32 v87, v18, 0x3f07dc22, v184
	v_fmaak_f32 v87, v18, v87, 0x3f35f0e3
	v_fmaak_f32 v87, v18, v87, 0xbe11a98e
	v_fmaak_f32 v87, v18, v87, 0x3e027906
	v_mul_f32_e32 v18, v18, v87
	v_mul_f32_e32 v87, v88, v88
	v_mul_f32_e32 v87, 0xbf38aa3b, v87
	v_exp_f32_e32 v87, v87
	v_pk_add_f32 v[24:25], v[10:11], v[24:25]
	v_mul_f32_e32 v18, v87, v18
	v_mul_f32_e32 v87, v88, v18
	v_fma_f32 v18, -v88, v18, v88
	v_cndmask_b32_e32 v18, v18, v87, vcc
	v_mul_f32_e32 v18, v84, v18
	v_fma_f32 v84, |v89|, s33, 1.0
	v_rcp_f32_e32 v84, v84
	v_cmp_gt_f32_e32 vcc, 0, v89
	v_fmamk_f32 v87, v84, 0x3f07dc22, v184
	v_fmaak_f32 v87, v84, v87, 0x3f35f0e3
	v_fmaak_f32 v87, v84, v87, 0xbe11a98e
	v_fmaak_f32 v87, v84, v87, 0x3e027906
	v_mul_f32_e32 v84, v84, v87
	v_mul_f32_e32 v87, v89, v89
	v_mul_f32_e32 v87, 0xbf38aa3b, v87
	v_exp_f32_e32 v87, v87
	s_nop 0
	v_mul_f32_e32 v84, v87, v84
	v_mul_f32_e32 v87, v89, v84
	v_fma_f32 v84, -v89, v84, v89
	v_cndmask_b32_e32 v84, v84, v87, vcc
	v_mul_f32_e32 v84, v85, v84
	v_cvt_pk_bf16_f32 v84, v18, v84
	v_fma_f32 v18, |v24|, s33, 1.0
	v_rcp_f32_e32 v18, v18
	v_cmp_gt_f32_e32 vcc, 0, v24
	v_fmamk_f32 v85, v18, 0x3f07dc22, v184
	v_fmaak_f32 v85, v18, v85, 0x3f35f0e3
	v_fmaak_f32 v85, v18, v85, 0xbe11a98e
	v_fmaak_f32 v85, v18, v85, 0x3e027906
	v_mul_f32_e32 v18, v18, v85
	v_mul_f32_e32 v85, v24, v24
	v_mul_f32_e32 v85, 0xbf38aa3b, v85
	v_exp_f32_e32 v85, v85
	s_nop 0
	v_mul_f32_e32 v18, v85, v18
	v_mul_f32_e32 v85, v24, v18
	v_fma_f32 v18, -v24, v18, v24
	v_fma_f32 v24, |v25|, s33, 1.0
	v_rcp_f32_e32 v24, v24
	v_cndmask_b32_e32 v18, v18, v85, vcc
	v_mul_f32_e32 v18, v78, v18
	v_cmp_gt_f32_e32 vcc, 0, v25
	v_fmamk_f32 v78, v24, 0x3f07dc22, v184
	v_fmaak_f32 v78, v24, v78, 0x3f35f0e3
	v_fmaak_f32 v78, v24, v78, 0xbe11a98e
	v_fmaak_f32 v78, v24, v78, 0x3e027906
	v_mul_f32_e32 v24, v24, v78
	v_mul_f32_e32 v78, v25, v25
	v_mul_f32_e32 v78, 0xbf38aa3b, v78
	v_exp_f32_e32 v78, v78
	s_nop 0
	v_mul_f32_e32 v24, v78, v24
	v_mul_f32_e32 v78, v25, v24
	v_fma_f32 v24, -v25, v24, v25
	v_cndmask_b32_e32 v24, v24, v78, vcc
	v_mul_f32_e32 v24, v79, v24
	v_cvt_pk_bf16_f32 v85, v18, v24
	v_mad_i64_i32 v[24:25], s[0:1], s16, v196, v[16:17]
	global_store_dwordx2 v[24:25], v[84:85], off
	v_pk_mul_f32 v[24:25], v[46:47], v[72:73]
	v_pk_mul_f32 v[78:79], v[44:45], v[70:71]
	v_pk_fma_f32 v[24:25], v[6:7], v[76:77], v[24:25]
	v_pk_fma_f32 v[76:77], v[4:5], v[74:75], v[78:79]
	v_lshlrev_b32_e32 v74, 16, v68
	v_and_b32_e32 v75, 0xffff0000, v68
	v_lshlrev_b32_e32 v78, 16, v69
	v_and_b32_e32 v79, 0xffff0000, v69
	v_pk_fma_f32 v[68:69], v[48:49], v[74:75], v[76:77]
	v_pk_mul_f32 v[76:77], v[12:13], v[20:21]
	v_pk_add_f32 v[84:85], v[52:53], v[68:69]
	v_pk_mul_f32 v[68:69], v[14:15], v[22:23]
	v_pk_fma_f32 v[80:81], v[0:1], v[80:81], v[76:77]
	v_pk_fma_f32 v[82:83], v[2:3], v[82:83], v[68:69]
	v_lshlrev_b32_e32 v68, 16, v26
	v_and_b32_e32 v69, 0xffff0000, v26
	v_pk_fma_f32 v[80:81], v[40:41], v[68:69], v[80:81]
	v_lshlrev_b32_e32 v76, 16, v27
	v_pk_add_f32 v[80:81], v[8:9], v[80:81]
	v_and_b32_e32 v77, 0xffff0000, v27
	v_fma_f32 v18, |v80|, s33, 1.0
	v_rcp_f32_e32 v18, v18
	v_pk_fma_f32 v[26:27], v[42:43], v[76:77], v[82:83]
	v_cmp_gt_f32_e32 vcc, 0, v80
	v_pk_add_f32 v[26:27], v[10:11], v[26:27]
; __device__ __forceinline__ unsigned cvt_pk_bf16(float lo, float hi) { unsigned r; asm volatile("v_cvt_pk_bf16_f32 %0, %1, %2" : "=v"(r) : "v"(lo), "v"(hi)); return r; }
; #define BF4(u) ((f32x4){__uint_as_float((u).x << 16), __uint_as_float((u).x & 0xffff0000u), __uint_as_float((u).y << 16), __uint_as_float((u).y & 0xffff0000u)})
; __device__ __forceinline__ float gelu_erf(float v) {
;     const float av = __builtin_fabsf(v), d = av * 0.2316418882f + 1.0f, t = __builtin_amdgcn_rcpf(d);
;     float q = t * 0.5307027145f + (-0.7265760135f); q = q * t + 0.7107068705f; q = q * t + (-0.142248368f); q = q * t + 0.127414796f; q = q * t;
;     const float e = __builtin_amdgcn_exp2f((v * v) * (-0.72134752044f));
;     const float m = v * (q * e), r = v - m;
;     return v < 0.f ? m : r;
; }
; __global__ void __launch_bounds__(512, 2) mega_fwd(Params p) {
;     ...
;                         for (int i = 0; i < 8; ++i) {
;                             const f32x4 av = wa[0] * BF4(ra[i]) + wa[1] * BF4(ra[i + 1]) + wa[2] * BF4(ra[i + 2]) + ba;
;                             const f32x4 gv = wg[0] * BF4(rg[i]) + wg[1] * BF4(rg[i + 1]) + wg[2] * BF4(rg[i + 2]) + bg;
;                             u32x2 w; w.x = cvt_pk_bf16(av[0] * gelu_erf(gv[0]), av[1] * gelu_erf(gv[1])); w.y = cvt_pk_bf16(av[2] * gelu_erf(gv[2]), av[3] * gelu_erf(gv[3]));
;                             *(u32x2*)(U + (size_t)(row0 + r0 + i) * DFF + col) = w;
	v_fmamk_f32 v82, v18, 0x3f07dc22, v184
	v_fmaak_f32 v82, v18, v82, 0x3f35f0e3
	v_fmaak_f32 v82, v18, v82, 0xbe11a98e
	v_fmaak_f32 v82, v18, v82, 0x3e027906
	v_mul_f32_e32 v18, v18, v82
	v_mul_f32_e32 v82, v80, v80
	v_mul_f32_e32 v82, 0xbf38aa3b, v82
	v_exp_f32_e32 v82, v82
	v_pk_fma_f32 v[24:25], v[50:51], v[78:79], v[24:25]
	s_or_b32 s0, s16, 1
	v_pk_add_f32 v[24:25], v[54:55], v[24:25]
	v_mul_f32_e32 v18, v82, v18
	v_mul_f32_e32 v82, v80, v18
	v_fma_f32 v18, -v80, v18, v80
	v_fma_f32 v80, |v81|, s33, 1.0
	v_rcp_f32_e32 v80, v80
	v_cndmask_b32_e32 v18, v18, v82, vcc
	v_cmp_gt_f32_e32 vcc, 0, v81
	v_mul_f32_e32 v18, v84, v18
	v_fmamk_f32 v82, v80, 0x3f07dc22, v184
	v_fmaak_f32 v82, v80, v82, 0x3f35f0e3
	v_fmaak_f32 v82, v80, v82, 0xbe11a98e
	v_fmaak_f32 v82, v80, v82, 0x3e027906
	v_mul_f32_e32 v80, v80, v82
	v_mul_f32_e32 v82, v81, v81
	v_mul_f32_e32 v82, 0xbf38aa3b, v82
	v_exp_f32_e32 v82, v82
	s_nop 0
	v_mul_f32_e32 v80, v82, v80
	v_mul_f32_e32 v82, v81, v80
	v_fma_f32 v80, -v81, v80, v81
	v_cndmask_b32_e32 v80, v80, v82, vcc
	v_mul_f32_e32 v80, v85, v80
	v_cvt_pk_bf16_f32 v80, v18, v80
	v_fma_f32 v18, |v26|, s33, 1.0
	v_rcp_f32_e32 v18, v18
	v_cmp_gt_f32_e32 vcc, 0, v26
	v_fmamk_f32 v81, v18, 0x3f07dc22, v184
	v_fmaak_f32 v81, v18, v81, 0x3f35f0e3
	v_fmaak_f32 v81, v18, v81, 0xbe11a98e
	v_fmaak_f32 v81, v18, v81, 0x3e027906
	v_mul_f32_e32 v18, v18, v81
	v_mul_f32_e32 v81, v26, v26
	v_mul_f32_e32 v81, 0xbf38aa3b, v81
	v_exp_f32_e32 v81, v81
	s_nop 0
	v_mul_f32_e32 v18, v81, v18
	v_mul_f32_e32 v81, v26, v18
	v_fma_f32 v18, -v26, v18, v26
	v_cndmask_b32_e32 v18, v18, v81, vcc
	v_mul_f32_e32 v18, v24, v18
	v_fma_f32 v24, |v27|, s33, 1.0
	v_rcp_f32_e32 v24, v24
	v_cmp_gt_f32_e32 vcc, 0, v27
	v_fmamk_f32 v26, v24, 0x3f07dc22, v184
	v_fmaak_f32 v26, v24, v26, 0x3f35f0e3
	v_fmaak_f32 v26, v24, v26, 0xbe11a98e
	v_fmaak_f32 v26, v24, v26, 0x3e027906
	v_mul_f32_e32 v24, v24, v26
	v_mul_f32_e32 v26, v27, v27
	v_mul_f32_e32 v26, 0xbf38aa3b, v26
	v_exp_f32_e32 v26, v26
	s_nop 0
	v_mul_f32_e32 v24, v26, v24
	v_mul_f32_e32 v26, v27, v24
	v_fma_f32 v24, -v27, v24, v27
	v_cndmask_b32_e32 v24, v24, v26, vcc
	v_mul_f32_e32 v24, v25, v24
	v_cvt_pk_bf16_f32 v81, v18, v24
	v_mad_i64_i32 v[24:25], s[0:1], s0, v196, v[16:17]
	global_store_dwordx2 v[24:25], v[80:81], off
	v_pk_mul_f32 v[24:25], v[46:47], v[78:79]
	v_pk_mul_f32 v[26:27], v[44:45], v[74:75]
	v_pk_fma_f32 v[24:25], v[6:7], v[72:73], v[24:25]
	v_pk_fma_f32 v[72:73], v[4:5], v[70:71], v[26:27]
	v_lshlrev_b32_e32 v26, 16, v66
	v_and_b32_e32 v27, 0xffff0000, v66
	v_lshlrev_b32_e32 v70, 16, v67
	v_and_b32_e32 v71, 0xffff0000, v67
	v_pk_fma_f32 v[66:67], v[48:49], v[26:27], v[72:73]
	v_pk_fma_f32 v[24:25], v[50:51], v[70:71], v[24:25]
	v_pk_add_f32 v[80:81], v[52:53], v[66:67]
	v_pk_add_f32 v[72:73], v[54:55], v[24:25]
	v_pk_mul_f32 v[24:25], v[14:15], v[76:77]
	v_pk_mul_f32 v[66:67], v[12:13], v[68:69]
	v_pk_fma_f32 v[22:23], v[2:3], v[22:23], v[24:25]
	v_pk_fma_f32 v[20:21], v[0:1], v[20:21], v[66:67]
	v_lshlrev_b32_e32 v24, 16, v28
	v_and_b32_e32 v25, 0xffff0000, v28
	v_lshlrev_b32_e32 v66, 16, v29
	v_and_b32_e32 v67, 0xffff0000, v29
	v_pk_fma_f32 v[28:29], v[40:41], v[24:25], v[20:21]
	v_pk_fma_f32 v[20:21], v[42:43], v[66:67], v[22:23]
	v_pk_add_f32 v[22:23], v[8:9], v[28:29]
	v_pk_add_f32 v[20:21], v[10:11], v[20:21]
	v_fma_f32 v18, |v22|, s33, 1.0
	v_rcp_f32_e32 v18, v18
	v_cmp_gt_f32_e32 vcc, 0, v22
	s_or_b32 s0, s16, 2
	v_fmamk_f32 v28, v18, 0x3f07dc22, v184
	v_fmaak_f32 v28, v18, v28, 0x3f35f0e3
	v_fmaak_f32 v28, v18, v28, 0xbe11a98e
	v_fmaak_f32 v28, v18, v28, 0x3e027906
	v_mul_f32_e32 v18, v18, v28
	v_mul_f32_e32 v28, v22, v22
	v_mul_f32_e32 v28, 0xbf38aa3b, v28
	v_exp_f32_e32 v28, v28
	s_nop 0
	v_mul_f32_e32 v18, v28, v18
	v_mul_f32_e32 v28, v22, v18
	v_fma_f32 v18, -v22, v18, v22
	v_fma_f32 v22, |v23|, s33, 1.0
	v_rcp_f32_e32 v22, v22
	v_cndmask_b32_e32 v18, v18, v28, vcc
	v_cmp_gt_f32_e32 vcc, 0, v23
	v_mul_f32_e32 v18, v80, v18
	v_fmamk_f32 v28, v22, 0x3f07dc22, v184
	v_fmaak_f32 v28, v22, v28, 0x3f35f0e3
	v_fmaak_f32 v28, v22, v28, 0xbe11a98e
	v_fmaak_f32 v28, v22, v28, 0x3e027906
	v_mul_f32_e32 v22, v22, v28
	v_mul_f32_e32 v28, v23, v23
	v_mul_f32_e32 v28, 0xbf38aa3b, v28
	v_exp_f32_e32 v28, v28
	s_nop 0
	v_mul_f32_e32 v22, v28, v22
	v_mul_f32_e32 v28, v23, v22
	v_fma_f32 v22, -v23, v22, v23
	v_cndmask_b32_e32 v22, v22, v28, vcc
	v_mul_f32_e32 v22, v81, v22
	v_cvt_pk_bf16_f32 v22, v18, v22
	v_fma_f32 v18, |v20|, s33, 1.0
	v_rcp_f32_e32 v18, v18
	v_cmp_gt_f32_e32 vcc, 0, v20
	v_fmamk_f32 v23, v18, 0x3f07dc22, v184
	v_fmaak_f32 v23, v18, v23, 0x3f35f0e3
	v_fmaak_f32 v23, v18, v23, 0xbe11a98e
	v_fmaak_f32 v23, v18, v23, 0x3e027906
	v_mul_f32_e32 v18, v18, v23
	v_mul_f32_e32 v23, v20, v20
	v_mul_f32_e32 v23, 0xbf38aa3b, v23
	v_exp_f32_e32 v23, v23
	s_nop 0
	v_mul_f32_e32 v18, v23, v18
	v_mul_f32_e32 v23, v20, v18
	v_fma_f32 v18, -v20, v18, v20
	v_fma_f32 v20, |v21|, s33, 1.0
	v_rcp_f32_e32 v20, v20
	v_cndmask_b32_e32 v18, v18, v23, vcc
	v_cmp_gt_f32_e32 vcc, 0, v21
	v_mul_f32_e32 v18, v72, v18
	v_fmamk_f32 v23, v20, 0x3f07dc22, v184
	v_fmaak_f32 v23, v20, v23, 0x3f35f0e3
	v_fmaak_f32 v23, v20, v23, 0xbe11a98e
	v_fmaak_f32 v23, v20, v23, 0x3e027906
	v_mul_f32_e32 v20, v20, v23
	v_mul_f32_e32 v23, v21, v21
	v_mul_f32_e32 v23, 0xbf38aa3b, v23
	v_exp_f32_e32 v23, v23
	s_nop 0
	v_mul_f32_e32 v20, v23, v20
	v_mul_f32_e32 v23, v21, v20
	v_fma_f32 v20, -v21, v20, v21
	v_cndmask_b32_e32 v20, v20, v23, vcc
	v_mul_f32_e32 v20, v73, v20
	v_cvt_pk_bf16_f32 v23, v18, v20
	v_mad_i64_i32 v[20:21], s[0:1], s0, v196, v[16:17]
	global_store_dwordx2 v[20:21], v[22:23], off
	v_pk_mul_f32 v[20:21], v[46:47], v[70:71]
; __device__ __forceinline__ unsigned cvt_pk_bf16(float lo, float hi) { unsigned r; asm volatile("v_cvt_pk_bf16_f32 %0, %1, %2" : "=v"(r) : "v"(lo), "v"(hi)); return r; }
; #define BF4(u) ((f32x4){__uint_as_float((u).x << 16), __uint_as_float((u).x & 0xffff0000u), __uint_as_float((u).y << 16), __uint_as_float((u).y & 0xffff0000u)})
; __device__ __forceinline__ float gelu_erf(float v) {
;     const float av = __builtin_fabsf(v), d = av * 0.2316418882f + 1.0f, t = __builtin_amdgcn_rcpf(d);
;     float q = t * 0.5307027145f + (-0.7265760135f); q = q * t + 0.7107068705f; q = q * t + (-0.142248368f); q = q * t + 0.127414796f; q = q * t;
;     const float e = __builtin_amdgcn_exp2f((v * v) * (-0.72134752044f));
;     const float m = v * (q * e), r = v - m;
;     return v < 0.f ? m : r;
; }
; __global__ void __launch_bounds__(512, 2) mega_fwd(Params p) {
;     ...
;                         for (int i = 0; i < 8; ++i) {
;                             const f32x4 av = wa[0] * BF4(ra[i]) + wa[1] * BF4(ra[i + 1]) + wa[2] * BF4(ra[i + 2]) + ba;
;                             const f32x4 gv = wg[0] * BF4(rg[i]) + wg[1] * BF4(rg[i + 1]) + wg[2] * BF4(rg[i + 2]) + bg;
;                             u32x2 w; w.x = cvt_pk_bf16(av[0] * gelu_erf(gv[0]), av[1] * gelu_erf(gv[1])); w.y = cvt_pk_bf16(av[2] * gelu_erf(gv[2]), av[3] * gelu_erf(gv[3]));
;                             *(u32x2*)(U + (size_t)(row0 + r0 + i) * DFF + col) = w;
	v_pk_mul_f32 v[22:23], v[44:45], v[26:27]
	v_pk_fma_f32 v[20:21], v[6:7], v[78:79], v[20:21]
	v_pk_fma_f32 v[28:29], v[4:5], v[74:75], v[22:23]
	v_lshlrev_b32_e32 v22, 16, v64
	v_and_b32_e32 v23, 0xffff0000, v64
	v_lshlrev_b32_e32 v64, 16, v65
	v_and_b32_e32 v65, 0xffff0000, v65
	v_pk_fma_f32 v[28:29], v[48:49], v[22:23], v[28:29]
	v_pk_fma_f32 v[20:21], v[50:51], v[64:65], v[20:21]
	v_pk_add_f32 v[74:75], v[52:53], v[28:29]
	v_pk_add_f32 v[72:73], v[54:55], v[20:21]
	v_pk_mul_f32 v[20:21], v[14:15], v[66:67]
	v_pk_mul_f32 v[28:29], v[12:13], v[24:25]
	v_pk_fma_f32 v[76:77], v[2:3], v[76:77], v[20:21]
	v_pk_fma_f32 v[68:69], v[0:1], v[68:69], v[28:29]
	v_lshlrev_b32_e32 v20, 16, v30
	v_and_b32_e32 v21, 0xffff0000, v30
	v_pk_fma_f32 v[68:69], v[40:41], v[20:21], v[68:69]
	v_lshlrev_b32_e32 v28, 16, v31
	v_pk_add_f32 v[68:69], v[8:9], v[68:69]
	v_and_b32_e32 v29, 0xffff0000, v31
	v_fma_f32 v18, |v68|, s33, 1.0
	v_rcp_f32_e32 v18, v18
	v_pk_fma_f32 v[30:31], v[42:43], v[28:29], v[76:77]
	v_cmp_gt_f32_e32 vcc, 0, v68
	v_pk_add_f32 v[30:31], v[10:11], v[30:31]
	v_fmamk_f32 v76, v18, 0x3f07dc22, v184
	v_fmaak_f32 v76, v18, v76, 0x3f35f0e3
	v_fmaak_f32 v76, v18, v76, 0xbe11a98e
	v_fmaak_f32 v76, v18, v76, 0x3e027906
	v_mul_f32_e32 v18, v18, v76
	v_mul_f32_e32 v76, v68, v68
	v_mul_f32_e32 v76, 0xbf38aa3b, v76
	v_exp_f32_e32 v76, v76
	s_or_b32 s0, s16, 3
	v_mul_f32_e32 v18, v76, v18
	v_mul_f32_e32 v76, v68, v18
	v_fma_f32 v18, -v68, v18, v68
	v_fma_f32 v68, |v69|, s33, 1.0
	v_rcp_f32_e32 v68, v68
	v_cndmask_b32_e32 v18, v18, v76, vcc
	v_mul_f32_e32 v18, v74, v18
	v_cmp_gt_f32_e32 vcc, 0, v69
	v_fmamk_f32 v74, v68, 0x3f07dc22, v184
	v_fmaak_f32 v74, v68, v74, 0x3f35f0e3
	v_fmaak_f32 v74, v68, v74, 0xbe11a98e
	v_fmaak_f32 v74, v68, v74, 0x3e027906
	v_mul_f32_e32 v68, v68, v74
	v_mul_f32_e32 v74, v69, v69
	v_mul_f32_e32 v74, 0xbf38aa3b, v74
	v_exp_f32_e32 v74, v74
	s_nop 0
	v_mul_f32_e32 v68, v74, v68
	v_mul_f32_e32 v74, v69, v68
	v_fma_f32 v68, -v69, v68, v69
	v_cndmask_b32_e32 v68, v68, v74, vcc
	v_mul_f32_e32 v68, v75, v68
	v_cvt_pk_bf16_f32 v68, v18, v68
	v_fma_f32 v18, |v30|, s33, 1.0
	v_rcp_f32_e32 v18, v18
	v_cmp_gt_f32_e32 vcc, 0, v30
	v_fmamk_f32 v69, v18, 0x3f07dc22, v184
	v_fmaak_f32 v69, v18, v69, 0x3f35f0e3
	v_fmaak_f32 v69, v18, v69, 0xbe11a98e
	v_fmaak_f32 v69, v18, v69, 0x3e027906
	v_mul_f32_e32 v18, v18, v69
	v_mul_f32_e32 v69, v30, v30
	v_mul_f32_e32 v69, 0xbf38aa3b, v69
	v_exp_f32_e32 v69, v69
	s_nop 0
	v_mul_f32_e32 v18, v69, v18
	v_mul_f32_e32 v69, v30, v18
	v_fma_f32 v18, -v30, v18, v30
	v_fma_f32 v30, |v31|, s33, 1.0
	v_rcp_f32_e32 v30, v30
	v_cndmask_b32_e32 v18, v18, v69, vcc
	v_cmp_gt_f32_e32 vcc, 0, v31
	v_mul_f32_e32 v18, v72, v18
	v_fmamk_f32 v69, v30, 0x3f07dc22, v184
	v_fmaak_f32 v69, v30, v69, 0x3f35f0e3
	v_fmaak_f32 v69, v30, v69, 0xbe11a98e
	v_fmaak_f32 v69, v30, v69, 0x3e027906
	v_mul_f32_e32 v30, v30, v69
	v_mul_f32_e32 v69, v31, v31
	v_mul_f32_e32 v69, 0xbf38aa3b, v69
	v_exp_f32_e32 v69, v69
	s_nop 0
	v_mul_f32_e32 v30, v69, v30
	v_mul_f32_e32 v69, v31, v30
	v_fma_f32 v30, -v31, v30, v31
	v_cndmask_b32_e32 v30, v30, v69, vcc
	v_mul_f32_e32 v30, v73, v30
	v_cvt_pk_bf16_f32 v69, v18, v30
	v_mad_i64_i32 v[30:31], s[0:1], s0, v196, v[16:17]
	global_store_dwordx2 v[30:31], v[68:69], off
	v_pk_mul_f32 v[30:31], v[46:47], v[64:65]
	v_pk_mul_f32 v[72:73], v[12:13], v[20:21]
	v_pk_fma_f32 v[30:31], v[6:7], v[70:71], v[30:31]
	v_pk_mul_f32 v[70:71], v[14:15], v[28:29]
	v_pk_mul_f32 v[68:69], v[44:45], v[22:23]
	v_pk_fma_f32 v[66:67], v[2:3], v[66:67], v[70:71]
	v_pk_fma_f32 v[70:71], v[0:1], v[24:25], v[72:73]
	v_lshlrev_b32_e32 v24, 16, v32
	v_and_b32_e32 v25, 0xffff0000, v32
	v_pk_fma_f32 v[70:71], v[40:41], v[24:25], v[70:71]
	v_pk_fma_f32 v[68:69], v[4:5], v[26:27], v[68:69]
	v_pk_add_f32 v[70:71], v[8:9], v[70:71]
	v_lshlrev_b32_e32 v26, 16, v62
	v_fma_f32 v18, |v70|, s33, 1.0
	v_rcp_f32_e32 v18, v18
	v_and_b32_e32 v27, 0xffff0000, v62
	v_pk_fma_f32 v[68:69], v[48:49], v[26:27], v[68:69]
	v_cmp_gt_f32_e32 vcc, 0, v70
	v_fmamk_f32 v72, v18, 0x3f07dc22, v184
	v_fmaak_f32 v72, v18, v72, 0x3f35f0e3
	v_fmaak_f32 v72, v18, v72, 0xbe11a98e
	v_fmaak_f32 v72, v18, v72, 0x3e027906
	v_mul_f32_e32 v18, v18, v72
	v_mul_f32_e32 v72, v70, v70
	v_mul_f32_e32 v72, 0xbf38aa3b, v72
	v_exp_f32_e32 v72, v72
	v_pk_add_f32 v[68:69], v[52:53], v[68:69]
	v_lshlrev_b32_e32 v32, 16, v33
	v_and_b32_e32 v33, 0xffff0000, v33
	v_mul_f32_e32 v18, v72, v18
	v_mul_f32_e32 v72, v70, v18
	v_fma_f32 v18, -v70, v18, v70
	v_cndmask_b32_e32 v18, v18, v72, vcc
	v_mul_f32_e32 v18, v68, v18
	v_fma_f32 v68, |v71|, s33, 1.0
	v_rcp_f32_e32 v68, v68
	v_cmp_gt_f32_e32 vcc, 0, v71
	v_pk_fma_f32 v[66:67], v[42:43], v[32:33], v[66:67]
	v_lshlrev_b32_e32 v62, 16, v63
	v_fmamk_f32 v70, v68, 0x3f07dc22, v184
	v_fmaak_f32 v70, v68, v70, 0x3f35f0e3
	v_fmaak_f32 v70, v68, v70, 0xbe11a98e
	v_fmaak_f32 v70, v68, v70, 0x3e027906
	v_mul_f32_e32 v68, v68, v70
	v_mul_f32_e32 v70, v71, v71
	v_mul_f32_e32 v70, 0xbf38aa3b, v70
	v_exp_f32_e32 v70, v70
	v_pk_add_f32 v[66:67], v[10:11], v[66:67]
	v_and_b32_e32 v63, 0xffff0000, v63
	v_pk_fma_f32 v[30:31], v[50:51], v[62:63], v[30:31]
	v_mul_f32_e32 v68, v70, v68
	v_mul_f32_e32 v70, v71, v68
	v_fma_f32 v68, -v71, v68, v71
	v_cndmask_b32_e32 v68, v68, v70, vcc
	v_mul_f32_e32 v68, v69, v68
	v_cvt_pk_bf16_f32 v68, v18, v68
	v_fma_f32 v18, |v66|, s33, 1.0
	v_rcp_f32_e32 v18, v18
	v_cmp_gt_f32_e32 vcc, 0, v66
	v_pk_add_f32 v[30:31], v[54:55], v[30:31]
	s_or_b32 s0, s16, 4
	v_fmamk_f32 v69, v18, 0x3f07dc22, v184
	v_fmaak_f32 v69, v18, v69, 0x3f35f0e3
	v_fmaak_f32 v69, v18, v69, 0xbe11a98e
	v_fmaak_f32 v69, v18, v69, 0x3e027906
; __device__ __forceinline__ unsigned cvt_pk_bf16(float lo, float hi) { unsigned r; asm volatile("v_cvt_pk_bf16_f32 %0, %1, %2" : "=v"(r) : "v"(lo), "v"(hi)); return r; }
; #define BF4(u) ((f32x4){__uint_as_float((u).x << 16), __uint_as_float((u).x & 0xffff0000u), __uint_as_float((u).y << 16), __uint_as_float((u).y & 0xffff0000u)})
; __device__ __forceinline__ float gelu_erf(float v) {
;     const float av = __builtin_fabsf(v), d = av * 0.2316418882f + 1.0f, t = __builtin_amdgcn_rcpf(d);
;     float q = t * 0.5307027145f + (-0.7265760135f); q = q * t + 0.7107068705f; q = q * t + (-0.142248368f); q = q * t + 0.127414796f; q = q * t;
;     const float e = __builtin_amdgcn_exp2f((v * v) * (-0.72134752044f));
;     const float m = v * (q * e), r = v - m;
;     return v < 0.f ? m : r;
; }
; __global__ void __launch_bounds__(512, 2) mega_fwd(Params p) {
;     ...
;                         for (int i = 0; i < 8; ++i) {
;                             const f32x4 av = wa[0] * BF4(ra[i]) + wa[1] * BF4(ra[i + 1]) + wa[2] * BF4(ra[i + 2]) + ba;
;                             const f32x4 gv = wg[0] * BF4(rg[i]) + wg[1] * BF4(rg[i + 1]) + wg[2] * BF4(rg[i + 2]) + bg;
;                             u32x2 w; w.x = cvt_pk_bf16(av[0] * gelu_erf(gv[0]), av[1] * gelu_erf(gv[1])); w.y = cvt_pk_bf16(av[2] * gelu_erf(gv[2]), av[3] * gelu_erf(gv[3]));
;                             *(u32x2*)(U + (size_t)(row0 + r0 + i) * DFF + col) = w;
	v_mul_f32_e32 v18, v18, v69
	v_mul_f32_e32 v69, v66, v66
	v_mul_f32_e32 v69, 0xbf38aa3b, v69
	v_exp_f32_e32 v69, v69
	s_nop 0
	v_mul_f32_e32 v18, v69, v18
	v_mul_f32_e32 v69, v66, v18
	v_fma_f32 v18, -v66, v18, v66
	v_cndmask_b32_e32 v18, v18, v69, vcc
	v_mul_f32_e32 v18, v30, v18
	v_fma_f32 v30, |v67|, s33, 1.0
	v_rcp_f32_e32 v30, v30
	v_cmp_gt_f32_e32 vcc, 0, v67
	v_fmamk_f32 v66, v30, 0x3f07dc22, v184
	v_fmaak_f32 v66, v30, v66, 0x3f35f0e3
	v_fmaak_f32 v66, v30, v66, 0xbe11a98e
	v_fmaak_f32 v66, v30, v66, 0x3e027906
	v_mul_f32_e32 v30, v30, v66
	v_mul_f32_e32 v66, v67, v67
	v_mul_f32_e32 v66, 0xbf38aa3b, v66
	v_exp_f32_e32 v66, v66
	s_nop 0
	v_mul_f32_e32 v30, v66, v30
	v_mul_f32_e32 v66, v67, v30
	v_fma_f32 v30, -v67, v30, v67
	v_cndmask_b32_e32 v30, v30, v66, vcc
	v_mul_f32_e32 v30, v31, v30
	v_cvt_pk_bf16_f32 v69, v18, v30
	v_mad_i64_i32 v[30:31], s[0:1], s0, v196, v[16:17]
	v_pk_mul_f32 v[66:67], v[44:45], v[26:27]
	global_store_dwordx2 v[30:31], v[68:69], off
	v_pk_mul_f32 v[30:31], v[46:47], v[62:63]
	v_pk_fma_f32 v[66:67], v[4:5], v[22:23], v[66:67]
	v_lshlrev_b32_e32 v22, 16, v60
	v_and_b32_e32 v23, 0xffff0000, v60
	v_pk_fma_f32 v[64:65], v[6:7], v[64:65], v[30:31]
	v_lshlrev_b32_e32 v30, 16, v61
	v_and_b32_e32 v31, 0xffff0000, v61
	v_pk_fma_f32 v[66:67], v[48:49], v[22:23], v[66:67]
	v_pk_mul_f32 v[68:69], v[12:13], v[24:25]
	v_pk_fma_f32 v[60:61], v[50:51], v[30:31], v[64:65]
	v_pk_add_f32 v[64:65], v[52:53], v[66:67]
	v_pk_mul_f32 v[66:67], v[14:15], v[32:33]
	v_pk_fma_f32 v[68:69], v[0:1], v[20:21], v[68:69]
	v_lshlrev_b32_e32 v20, 16, v34
	v_and_b32_e32 v21, 0xffff0000, v34
	v_pk_fma_f32 v[66:67], v[2:3], v[28:29], v[66:67]
	v_lshlrev_b32_e32 v28, 16, v35
	v_and_b32_e32 v29, 0xffff0000, v35
	v_pk_fma_f32 v[68:69], v[40:41], v[20:21], v[68:69]
	v_pk_fma_f32 v[34:35], v[42:43], v[28:29], v[66:67]
	v_pk_add_f32 v[66:67], v[8:9], v[68:69]
	v_pk_add_f32 v[34:35], v[10:11], v[34:35]
	v_fma_f32 v18, |v66|, s33, 1.0
	v_rcp_f32_e32 v18, v18
	v_cmp_gt_f32_e32 vcc, 0, v66
	v_pk_add_f32 v[60:61], v[54:55], v[60:61]
	s_or_b32 s0, s16, 5
	v_fmamk_f32 v68, v18, 0x3f07dc22, v184
	v_fmaak_f32 v68, v18, v68, 0x3f35f0e3
	v_fmaak_f32 v68, v18, v68, 0xbe11a98e
	v_fmaak_f32 v68, v18, v68, 0x3e027906
	v_mul_f32_e32 v18, v18, v68
	v_mul_f32_e32 v68, v66, v66
	v_mul_f32_e32 v68, 0xbf38aa3b, v68
	v_exp_f32_e32 v68, v68
	s_nop 0
	v_mul_f32_e32 v18, v68, v18
	v_mul_f32_e32 v68, v66, v18
	v_fma_f32 v18, -v66, v18, v66
	v_cndmask_b32_e32 v18, v18, v68, vcc
	v_mul_f32_e32 v18, v64, v18
	v_fma_f32 v64, |v67|, s33, 1.0
	v_rcp_f32_e32 v64, v64
	v_cmp_gt_f32_e32 vcc, 0, v67
	v_fmamk_f32 v66, v64, 0x3f07dc22, v184
	v_fmaak_f32 v66, v64, v66, 0x3f35f0e3
	v_fmaak_f32 v66, v64, v66, 0xbe11a98e
	v_fmaak_f32 v66, v64, v66, 0x3e027906
	v_mul_f32_e32 v64, v64, v66
	v_mul_f32_e32 v66, v67, v67
	v_mul_f32_e32 v66, 0xbf38aa3b, v66
	v_exp_f32_e32 v66, v66
	s_nop 0
	v_mul_f32_e32 v64, v66, v64
	v_mul_f32_e32 v66, v67, v64
	v_fma_f32 v64, -v67, v64, v67
	v_cndmask_b32_e32 v64, v64, v66, vcc
	v_mul_f32_e32 v64, v65, v64
	v_cvt_pk_bf16_f32 v64, v18, v64
	v_fma_f32 v18, |v34|, s33, 1.0
	v_rcp_f32_e32 v18, v18
	v_cmp_gt_f32_e32 vcc, 0, v34
	v_fmamk_f32 v65, v18, 0x3f07dc22, v184
	v_fmaak_f32 v65, v18, v65, 0x3f35f0e3
	v_fmaak_f32 v65, v18, v65, 0xbe11a98e
	v_fmaak_f32 v65, v18, v65, 0x3e027906
	v_mul_f32_e32 v18, v18, v65
	v_mul_f32_e32 v65, v34, v34
	v_mul_f32_e32 v65, 0xbf38aa3b, v65
	v_exp_f32_e32 v65, v65
	s_nop 0
	v_mul_f32_e32 v18, v65, v18
	v_mul_f32_e32 v65, v34, v18
	v_fma_f32 v18, -v34, v18, v34
	v_fma_f32 v34, |v35|, s33, 1.0
	v_rcp_f32_e32 v34, v34
	v_cndmask_b32_e32 v18, v18, v65, vcc
	v_mul_f32_e32 v18, v60, v18
	v_cmp_gt_f32_e32 vcc, 0, v35
	v_fmamk_f32 v60, v34, 0x3f07dc22, v184
	v_fmaak_f32 v60, v34, v60, 0x3f35f0e3
	v_fmaak_f32 v60, v34, v60, 0xbe11a98e
	v_fmaak_f32 v60, v34, v60, 0x3e027906
	v_mul_f32_e32 v34, v34, v60
	v_mul_f32_e32 v60, v35, v35
	v_mul_f32_e32 v60, 0xbf38aa3b, v60
	v_exp_f32_e32 v60, v60
	s_nop 0
	v_mul_f32_e32 v34, v60, v34
	v_mul_f32_e32 v60, v35, v34
	v_fma_f32 v34, -v35, v34, v35
	v_cndmask_b32_e32 v34, v34, v60, vcc
	v_mul_f32_e32 v34, v61, v34
	v_cvt_pk_bf16_f32 v65, v18, v34
	v_mad_i64_i32 v[34:35], s[0:1], s0, v196, v[16:17]
	global_store_dwordx2 v[34:35], v[64:65], off
	v_pk_mul_f32 v[34:35], v[46:47], v[30:31]
	v_pk_mul_f32 v[60:61], v[44:45], v[22:23]
	v_pk_fma_f32 v[62:63], v[6:7], v[62:63], v[34:35]
	v_lshlrev_b32_e32 v34, 16, v59
	v_and_b32_e32 v35, 0xffff0000, v59
	v_pk_mul_f32 v[64:65], v[12:13], v[20:21]
	v_pk_fma_f32 v[60:61], v[4:5], v[26:27], v[60:61]
	v_lshlrev_b32_e32 v26, 16, v58
	v_and_b32_e32 v27, 0xffff0000, v58
	v_pk_fma_f32 v[58:59], v[50:51], v[34:35], v[62:63]
	v_pk_mul_f32 v[62:63], v[14:15], v[28:29]
	v_pk_fma_f32 v[64:65], v[0:1], v[24:25], v[64:65]
	v_lshlrev_b32_e32 v24, 16, v36
	v_and_b32_e32 v25, 0xffff0000, v36
	v_pk_fma_f32 v[62:63], v[2:3], v[32:33], v[62:63]
	v_lshlrev_b32_e32 v32, 16, v37
	v_and_b32_e32 v33, 0xffff0000, v37
	v_pk_fma_f32 v[64:65], v[40:41], v[24:25], v[64:65]
	v_pk_fma_f32 v[36:37], v[42:43], v[32:33], v[62:63]
	v_pk_add_f32 v[62:63], v[8:9], v[64:65]
	v_pk_fma_f32 v[60:61], v[48:49], v[26:27], v[60:61]
	v_fma_f32 v18, |v62|, s33, 1.0
	v_rcp_f32_e32 v18, v18
	v_cmp_gt_f32_e32 vcc, 0, v62
	v_pk_add_f32 v[60:61], v[52:53], v[60:61]
	v_pk_add_f32 v[36:37], v[10:11], v[36:37]
	v_fmamk_f32 v64, v18, 0x3f07dc22, v184
	v_fmaak_f32 v64, v18, v64, 0x3f35f0e3
	v_fmaak_f32 v64, v18, v64, 0xbe11a98e
	v_fmaak_f32 v64, v18, v64, 0x3e027906
	v_mul_f32_e32 v18, v18, v64
	v_mul_f32_e32 v64, v62, v62
	v_mul_f32_e32 v64, 0xbf38aa3b, v64
	v_exp_f32_e32 v64, v64
	v_pk_mul_f32 v[12:13], v[12:13], v[24:25]
; __device__ __forceinline__ unsigned cvt_pk_bf16(float lo, float hi) { unsigned r; asm volatile("v_cvt_pk_bf16_f32 %0, %1, %2" : "=v"(r) : "v"(lo), "v"(hi)); return r; }
; #define BF4(u) ((f32x4){__uint_as_float((u).x << 16), __uint_as_float((u).x & 0xffff0000u), __uint_as_float((u).y << 16), __uint_as_float((u).y & 0xffff0000u)})
; __global__ void __launch_bounds__(512, 2) mega_fwd(Params p) {
;     ...
;                     for (int it = gw; it < nitems; it += NGW) {
;                         const int rr = it / 11, cgp = it - rr * 11, col = (cgp * 64 + lane) * 4, r0 = rr * 8;
;                         u32x2 ra[10], rg[10];
;                         const bool hp = (r0 & smask) != 0, hn = ((r0 + 8) & smask) != 0;
; #pragma unroll
;                         for (int i = 0; i < 10; ++i) {
;                             const bool ok = (i == 0) ? hp : (i == 9) ? hn : true;
;                             if (ok) { ra[i] = *(const u32x2*)(H + (size_t)(r0 - 1 + i) * NFF + col); rg[i] = *(const u32x2*)(H + (size_t)(r0 - 1 + i) * NFF + DFF + col); }
;                             else { ra[i] = (u32x2){0u, 0u}; rg[i] = (u32x2){0u, 0u}; }
;                         }
;                         f32x4 wa[3], wg[3];
; #pragma unroll
;                         for (int k = 0; k < 3; ++k) { wa[k] = *(const f32x4*)(cw + k * NFF + col); wg[k] = *(const f32x4*)(cw + k * NFF + DFF + col); }
;                         const f32x4 ba = *(const f32x4*)(cb + col), bg = *(const f32x4*)(cb + DFF + col);
;     ...
;                         for (int i = 0; i < 8; ++i) {
;                             const f32x4 av = wa[0] * BF4(ra[i]) + wa[1] * BF4(ra[i + 1]) + wa[2] * BF4(ra[i + 2]) + ba;
;                             const f32x4 gv = wg[0] * BF4(rg[i]) + wg[1] * BF4(rg[i + 1]) + wg[2] * BF4(rg[i + 2]) + bg;
;                             u32x2 w; w.x = cvt_pk_bf16(av[0] * gelu_erf(gv[0]), av[1] * gelu_erf(gv[1])); w.y = cvt_pk_bf16(av[2] * gelu_erf(gv[2]), av[3] * gelu_erf(gv[3]));
;                             *(u32x2*)(U + (size_t)(row0 + r0 + i) * DFF + col) = w;
	v_pk_mul_f32 v[14:15], v[14:15], v[32:33]
	v_pk_fma_f32 v[0:1], v[0:1], v[20:21], v[12:13]
	v_mul_f32_e32 v18, v64, v18
	v_mul_f32_e32 v64, v62, v18
	v_fma_f32 v18, -v62, v18, v62
	v_cndmask_b32_e32 v18, v18, v64, vcc
	v_mul_f32_e32 v18, v60, v18
	v_fma_f32 v60, |v63|, s33, 1.0
	v_rcp_f32_e32 v60, v60
	v_cmp_gt_f32_e32 vcc, 0, v63
	v_lshlrev_b32_e32 v12, 16, v38
	v_and_b32_e32 v13, 0xffff0000, v38
	v_fmamk_f32 v62, v60, 0x3f07dc22, v184
	v_fmaak_f32 v62, v60, v62, 0x3f35f0e3
	v_fmaak_f32 v62, v60, v62, 0xbe11a98e
	v_fmaak_f32 v62, v60, v62, 0x3e027906
	v_mul_f32_e32 v60, v60, v62
	v_mul_f32_e32 v62, v63, v63
	v_mul_f32_e32 v62, 0xbf38aa3b, v62
	v_exp_f32_e32 v62, v62
	v_pk_fma_f32 v[2:3], v[2:3], v[28:29], v[14:15]
	v_lshlrev_b32_e32 v14, 16, v39
	v_and_b32_e32 v15, 0xffff0000, v39
	v_mul_f32_e32 v60, v62, v60
	v_mul_f32_e32 v62, v63, v60
	v_fma_f32 v60, -v63, v60, v63
	v_cndmask_b32_e32 v60, v60, v62, vcc
	v_mul_f32_e32 v60, v61, v60
	v_cvt_pk_bf16_f32 v60, v18, v60
	v_fma_f32 v18, |v36|, s33, 1.0
	v_rcp_f32_e32 v18, v18
	v_pk_fma_f32 v[12:13], v[40:41], v[12:13], v[0:1]
	v_cmp_gt_f32_e32 vcc, 0, v36
	v_pk_fma_f32 v[0:1], v[42:43], v[14:15], v[2:3]
	v_fmamk_f32 v61, v18, 0x3f07dc22, v184
	v_fmaak_f32 v61, v18, v61, 0x3f35f0e3
	v_fmaak_f32 v61, v18, v61, 0xbe11a98e
	v_fmaak_f32 v61, v18, v61, 0x3e027906
	v_mul_f32_e32 v18, v18, v61
	v_mul_f32_e32 v61, v36, v36
	v_mul_f32_e32 v61, 0xbf38aa3b, v61
	v_exp_f32_e32 v61, v61
	v_pk_add_f32 v[2:3], v[8:9], v[12:13]
	v_pk_add_f32 v[58:59], v[54:55], v[58:59]
	v_fma_f32 v8, |v2|, s33, 1.0
	v_mul_f32_e32 v18, v61, v18
	v_mul_f32_e32 v61, v36, v18
	v_fma_f32 v18, -v36, v18, v36
	v_fma_f32 v36, |v37|, s33, 1.0
	v_rcp_f32_e32 v36, v36
	v_rcp_f32_e32 v8, v8
	v_cndmask_b32_e32 v18, v18, v61, vcc
	v_mul_f32_e32 v18, v58, v18
	v_fmamk_f32 v58, v36, 0x3f07dc22, v184
	v_fmaak_f32 v58, v36, v58, 0x3f35f0e3
	v_fmamk_f32 v9, v8, 0x3f07dc22, v184
	v_fmaak_f32 v58, v36, v58, 0xbe11a98e
	v_fmaak_f32 v9, v8, v9, 0x3f35f0e3
	v_fmaak_f32 v58, v36, v58, 0x3e027906
	v_fmaak_f32 v9, v8, v9, 0xbe11a98e
	v_mul_f32_e32 v36, v36, v58
	v_mul_f32_e32 v58, v37, v37
	v_fmaak_f32 v9, v8, v9, 0x3e027906
	v_mul_f32_e32 v58, 0xbf38aa3b, v58
	v_mul_f32_e32 v8, v8, v9
	v_mul_f32_e32 v9, v2, v2
	v_exp_f32_e32 v58, v58
	v_mul_f32_e32 v9, 0xbf38aa3b, v9
	v_exp_f32_e32 v9, v9
	v_pk_mul_f32 v[26:27], v[44:45], v[26:27]
	v_mul_f32_e32 v36, v58, v36
	v_mul_f32_e32 v58, v37, v36
	v_fma_f32 v36, -v37, v36, v37
	v_cmp_gt_f32_e32 vcc, 0, v37
	v_pk_mul_f32 v[34:35], v[46:47], v[34:35]
	v_pk_fma_f32 v[4:5], v[4:5], v[22:23], v[26:27]
	v_lshlrev_b32_e32 v22, 16, v56
	v_and_b32_e32 v23, 0xffff0000, v56
	v_mul_f32_e32 v8, v9, v8
	v_cndmask_b32_e32 v36, v36, v58, vcc
	v_pk_fma_f32 v[6:7], v[6:7], v[30:31], v[34:35]
	v_lshlrev_b32_e32 v26, 16, v57
	v_and_b32_e32 v27, 0xffff0000, v57
	v_pk_fma_f32 v[22:23], v[48:49], v[22:23], v[4:5]
	v_mul_f32_e32 v9, v2, v8
	v_fma_f32 v8, -v2, v8, v2
	v_cmp_gt_f32_e32 vcc, 0, v2
	v_pk_fma_f32 v[4:5], v[50:51], v[26:27], v[6:7]
	v_pk_add_f32 v[6:7], v[52:53], v[22:23]
	v_cndmask_b32_e32 v2, v8, v9, vcc
	v_mul_f32_e32 v2, v6, v2
	v_fma_f32 v6, |v3|, s33, 1.0
	v_rcp_f32_e32 v6, v6
	v_cmp_gt_f32_e32 vcc, 0, v3
	v_mul_f32_e32 v36, v59, v36
	s_or_b32 s0, s16, 6
	v_fmamk_f32 v8, v6, 0x3f07dc22, v184
	v_fmaak_f32 v8, v6, v8, 0x3f35f0e3
	v_fmaak_f32 v8, v6, v8, 0xbe11a98e
	v_fmaak_f32 v8, v6, v8, 0x3e027906
	v_mul_f32_e32 v6, v6, v8
	v_mul_f32_e32 v8, v3, v3
	v_mul_f32_e32 v8, 0xbf38aa3b, v8
	v_exp_f32_e32 v8, v8
	v_cvt_pk_bf16_f32 v61, v18, v36
	v_mad_i64_i32 v[36:37], s[0:1], s0, v196, v[16:17]
	v_mul_f32_e32 v6, v8, v6
	v_mul_f32_e32 v8, v3, v6
	v_fma_f32 v6, -v3, v6, v3
	v_cndmask_b32_e32 v3, v6, v8, vcc
	v_pk_add_f32 v[0:1], v[10:11], v[0:1]
	v_mul_f32_e32 v3, v7, v3
	global_store_dwordx2 v[36:37], v[60:61], off
	v_cvt_pk_bf16_f32 v2, v2, v3
	v_fma_f32 v3, |v0|, s33, 1.0
	v_rcp_f32_e32 v3, v3
	v_cmp_gt_f32_e32 vcc, 0, v0
	v_pk_add_f32 v[4:5], v[54:55], v[4:5]
	s_or_b32 s0, s16, 7
	v_fmamk_f32 v6, v3, 0x3f07dc22, v184
	v_fmaak_f32 v6, v3, v6, 0x3f35f0e3
	v_fmaak_f32 v6, v3, v6, 0xbe11a98e
	v_fmaak_f32 v6, v3, v6, 0x3e027906
	v_mul_f32_e32 v3, v3, v6
	v_mul_f32_e32 v6, v0, v0
	v_mul_f32_e32 v6, 0xbf38aa3b, v6
	v_exp_f32_e32 v6, v6
	s_cmp_lt_i32 s22, s10
	v_mul_f32_e32 v3, v6, v3
	v_mul_f32_e32 v6, v0, v3
	v_fma_f32 v3, -v0, v3, v0
	v_cndmask_b32_e32 v0, v3, v6, vcc
	v_fma_f32 v3, |v1|, s33, 1.0
	v_rcp_f32_e32 v3, v3
	v_mul_f32_e32 v0, v4, v0
	v_cmp_gt_f32_e32 vcc, 0, v1
	v_fmamk_f32 v4, v3, 0x3f07dc22, v184
	v_fmaak_f32 v4, v3, v4, 0x3f35f0e3
	v_fmaak_f32 v4, v3, v4, 0xbe11a98e
	v_fmaak_f32 v4, v3, v4, 0x3e027906
	v_mul_f32_e32 v3, v3, v4
	v_mul_f32_e32 v4, v1, v1
	v_mul_f32_e32 v4, 0xbf38aa3b, v4
	v_exp_f32_e32 v4, v4
	s_nop 0
	v_mul_f32_e32 v3, v4, v3
	v_mul_f32_e32 v4, v1, v3
	v_fma_f32 v3, -v1, v3, v1
	v_cndmask_b32_e32 v1, v3, v4, vcc
	v_mul_f32_e32 v1, v5, v1
	v_cvt_pk_bf16_f32 v3, v0, v1
	v_mad_i64_i32 v[0:1], s[0:1], s0, v196, v[16:17]
	global_store_dwordx2 v[0:1], v[2:3], off
	s_cbranch_scc0 .LBB0_1149
.LBB0_1144:
	s_mul_hi_i32 s0, s22, 0x2e8ba2e9
	s_lshr_b32 s1, s0, 31
	s_ashr_i32 s0, s0, 1
	s_add_i32 s0, s0, s1
	s_mul_i32 s1, s0, 0xfffff500
	s_lshl_b32 s0, s0, 3
	v_add_u32_e32 v70, s1, v86
	s_and_b32 s1, s0, s23
	s_cmp_eq_u32 s1, 0
	v_ashrrev_i32_e32 v71, 31, v70
	v_lshlrev_b64 v[132:133], 2, v[70:71]
	v_lshl_add_u64 v[134:135], s[40:41], 0, v[132:133]
	global_load_dwordx4 v[100:103], v[134:135], off
	v_lshl_add_u64 v[134:135], s[54:55], 0, v[132:133]
	global_load_dwordx4 v[104:107], v[134:135], off
	v_lshl_add_u64 v[134:135], s[6:7], 0, v[132:133]
	global_load_dwordx4 v[108:111], v[134:135], off
	v_lshl_add_u64 v[134:135], s[62:63], 0, v[132:133]
	global_load_dwordx4 v[112:115], v[134:135], off
	v_lshl_add_u64 v[134:135], s[12:13], 0, v[132:133]
	global_load_dwordx4 v[116:119], v[134:135], off
	v_lshl_add_u64 v[134:135], s[42:43], 0, v[132:133]
	global_load_dwordx4 v[120:123], v[134:135], off
	v_lshl_add_u64 v[134:135], s[50:51], 0, v[132:133]
	global_load_dwordx4 v[124:127], v[134:135], off
	v_lshl_add_u64 v[134:135], s[46:47], 0, v[132:133]
	global_load_dwordx4 v[128:131], v[134:135], off
	s_cbranch_scc1 .LBB0_1147
	s_add_i32 s1, s0, -1
	s_mul_hi_i32 s2, s1, 0x2c00
	s_mulk_i32 s1, 0x2c00
	s_add_u32 s8, s31, s1
	s_addc_u32 s9, s38, s2
	v_lshl_add_u64 v[0:1], v[70:71], 1, s[8:9]
	v_add_co_u32_e32 v2, vcc, 0x1000, v0
	s_nop 1
	v_addc_co_u32_e32 v3, vcc, 0, v1, vcc
	global_load_dwordx2 v[72:73], v[0:1], off
	s_nop 0
	global_load_dwordx2 v[0:1], v[2:3], off offset:1536
	s_cbranch_execnz .LBB0_1141
	s_branch .LBB0_1148
